# bundle + MoBA prep q/k source rows fetched by LDS-DMA with eight lanes per row
# speedup vs baseline: 1.0166x; 1.0022x over previous
.LBB0_390:
	s_bfe_u32 s1, s0, 0x40003
	s_and_b32 s8, s36, 0xfffff000
	s_lshl_b32 s35, s1, 8
	s_or_b32 s40, s35, s8
	v_add_u32_e32 v2, s40, v140
	v_ashrrev_i32_e32 v3, 31, v2
	s_and_b32 s34, s0, 7
	v_lshlrev_b64 v[2:3], 11, v[2:3]
	v_lshl_add_u64 v[2:3], s[24:25], 0, v[2:3]
	s_lshl_b32 s20, s34, 7
	v_lshl_add_u64 v[2:3], v[2:3], 0, s[20:21]
	v_lshl_add_u64 v[18:19], v[2:3], 0, v[104:105]
	global_load_dwordx4 v[2:5], v[18:19], off offset:1024
	global_load_dwordx4 v[6:9], v[18:19], off offset:1040
	global_load_dwordx4 v[10:13], v[18:19], off offset:1056
	global_load_dwordx4 v[14:17], v[18:19], off offset:1072
	v_or_b32_sdwa v114, s40, v1 dst_sel:DWORD dst_unused:UNUSED_PAD src0_sel:DWORD src1_sel:BYTE_0
	v_ashrrev_i32_e32 v115, 31, v114
	s_waitcnt vmcnt(0)
	ds_write_b16 v141, v2
	ds_write_b16_d16_hi v141, v2 offset:528
	ds_write_b16 v141, v3 offset:1056
	ds_write_b16_d16_hi v141, v3 offset:1584
	ds_write_b16 v141, v4 offset:2112
	ds_write_b16_d16_hi v141, v4 offset:2640
	ds_write_b16 v141, v5 offset:3168
	ds_write_b16_d16_hi v141, v5 offset:3696
	ds_write_b16 v141, v6 offset:4224
	ds_write_b16_d16_hi v141, v6 offset:4752
	ds_write_b16 v141, v7 offset:5280
	ds_write_b16_d16_hi v141, v7 offset:5808
	ds_write_b16 v141, v8 offset:6336
	ds_write_b16_d16_hi v141, v8 offset:6864
	ds_write_b16 v141, v9 offset:7392
	ds_write_b16_d16_hi v141, v9 offset:7920
	ds_write_b16 v141, v10 offset:8448
	ds_write_b16_d16_hi v141, v10 offset:8976
	ds_write_b16 v141, v11 offset:9504
	ds_write_b16_d16_hi v141, v11 offset:10032
	ds_write_b16 v141, v12 offset:10560
	ds_write_b16_d16_hi v141, v12 offset:11088
	ds_write_b16 v141, v13 offset:11616
	ds_write_b16_d16_hi v141, v13 offset:12144
	ds_write_b16 v141, v14 offset:12672
	ds_write_b16_d16_hi v141, v14 offset:13200
	ds_write_b16 v141, v15 offset:13728
	ds_write_b16_d16_hi v141, v15 offset:14256
	ds_write_b16 v141, v16 offset:14784
	ds_write_b16_d16_hi v141, v16 offset:15312
	ds_write_b16 v141, v17 offset:15840
	ds_write_b16_d16_hi v141, v17 offset:16368
	s_waitcnt lgkmcnt(0)
	s_barrier
	s_and_saveexec_b64 s[8:9], s[2:3]
	s_xor_b64 s[8:9], exec, s[8:9]
	v_lshlrev_b64 v[2:3], 11, v[114:115]
	v_lshl_add_u64 v[2:3], s[98:99], 0, v[2:3]
	s_or_saveexec_b64 s[8:9], s[8:9]
	v_mov_b64_e32 v[4:5], s[22:23]
	v_or_b32_e32 v116, s40, v1
	s_xor_b64 exec, exec, s[8:9]
	v_mov_b64_e32 v[2:3], s[14:15]
	v_mad_i64_i32 v[2:3], s[40:41], v116, s38, v[2:3]
	v_lshl_add_u64 v[2:3], v[2:3], 0, s[26:27]
	v_mov_b64_e32 v[4:5], s[18:19]
	s_or_b64 exec, exec, s[8:9]
	global_load_dwordx2 v[112:113], v[4:5], off
	s_lshl_b32 s8, s34, 6
	s_lshl_b32 s20, s8, 1
	v_lshl_add_u64 v[2:3], v[2:3], 0, s[20:21]
	v_readfirstlane_b32 s46, v1
	v_and_b32_e32 v239, 63, v1
	v_readfirstlane_b32 s42, v2
	v_readfirstlane_b32 s43, v3
	s_lshr_b32 s47, s46, 6
	s_cmpk_gt_u32 s46, 0xff
	s_movk_i32 s49, 0x1400
	s_cselect_b32 s49, 0x800, s49
	s_lshl_b32 s50, s49, 3
	s_mov_b32 s51, 0
	s_mul_i32 s48, s47, 0x2400
	s_add_i32 s48, s48, 0x19000
	s_sub_i32 s8, s47, 4
	s_mul_i32 s8, s8, 0x4100
	s_cmpk_gt_u32 s46, 0xff
	s_cselect_b32 s48, s8, s48
	v_lshrrev_b32_e32 v240, 3, v239
	v_and_b32_e32 v241, 7, v239
	v_lshl_add_u32 v239, v239, 7, s48
	v_mul_lo_u32 v240, v240, s49
	v_lshl_add_u32 v240, v241, 4, v240
	v_mov_b32_e32 v241, 0
	s_nop 0
	v_lshl_add_u64 v[240:241], s[42:43], 0, v[240:241]
	s_mov_b32 m0, s48
	s_nop 0
	global_load_lds_dwordx4 v[240:241], off
	v_lshl_add_u64 v[240:241], v[240:241], 0, s[50:51]
	s_add_i32 m0, s48, 0x400
	s_nop 0
	global_load_lds_dwordx4 v[240:241], off
	v_lshl_add_u64 v[240:241], v[240:241], 0, s[50:51]
	s_add_i32 m0, s48, 0x800
	s_nop 0
	global_load_lds_dwordx4 v[240:241], off
	v_lshl_add_u64 v[240:241], v[240:241], 0, s[50:51]
	s_add_i32 m0, s48, 0xc00
	s_nop 0
	global_load_lds_dwordx4 v[240:241], off
	v_lshl_add_u64 v[240:241], v[240:241], 0, s[50:51]
	s_add_i32 m0, s48, 0x1000
	s_nop 0
	global_load_lds_dwordx4 v[240:241], off
	v_lshl_add_u64 v[240:241], v[240:241], 0, s[50:51]
	s_add_i32 m0, s48, 0x1400
	s_nop 0
	global_load_lds_dwordx4 v[240:241], off
	v_lshl_add_u64 v[240:241], v[240:241], 0, s[50:51]
	s_add_i32 m0, s48, 0x1800
	s_nop 0
	global_load_lds_dwordx4 v[240:241], off
	v_lshl_add_u64 v[240:241], v[240:241], 0, s[50:51]
	s_add_i32 m0, s48, 0x1c00
	s_nop 0
	global_load_lds_dwordx4 v[240:241], off
	s_waitcnt vmcnt(8)
	global_load_dwordx4 v[46:49], v[112:113], off offset:48
	global_load_dwordx4 v[54:57], v[112:113], off offset:32
	global_load_dwordx4 v[58:61], v[112:113], off offset:16
	global_load_dwordx4 v[62:65], v[112:113], off
	global_load_dwordx4 v[30:33], v[112:113], off offset:112
	global_load_dwordx4 v[38:41], v[112:113], off offset:96
	global_load_dwordx4 v[42:45], v[112:113], off offset:80
	global_load_dwordx4 v[50:53], v[112:113], off offset:64
	global_load_dwordx4 v[14:17], v[112:113], off offset:176
	global_load_dwordx4 v[22:25], v[112:113], off offset:160
	global_load_dwordx4 v[26:29], v[112:113], off offset:144
	global_load_dwordx4 v[34:37], v[112:113], off offset:128
	global_load_dwordx4 v[2:5], v[112:113], off offset:240
	global_load_dwordx4 v[6:9], v[112:113], off offset:224
	global_load_dwordx4 v[10:13], v[112:113], off offset:208
	global_load_dwordx4 v[18:21], v[112:113], off offset:192
	s_waitcnt vmcnt(16)
	ds_read_b128 v[94:97], v239
	ds_read_b128 v[90:93], v239 offset:16
	ds_read_b128 v[86:89], v239 offset:32
	ds_read_b128 v[82:85], v239 offset:48
	ds_read_b128 v[78:81], v239 offset:64
	ds_read_b128 v[74:77], v239 offset:80
	ds_read_b128 v[70:73], v239 offset:96
	ds_read_b128 v[66:69], v239 offset:112
	s_waitcnt lgkmcnt(0)
	s_and_saveexec_b64 s[8:9], s[2:3]
	s_xor_b64 s[8:9], exec, s[8:9]
	v_lshlrev_b64 v[112:113], 10, v[114:115]
	v_lshl_add_u64 v[112:113], s[12:13], 0, v[112:113]
	s_andn2_saveexec_b64 s[8:9], s[8:9]
	v_ashrrev_i32_e32 v117, 31, v116
	v_lshlrev_b64 v[112:113], 11, v[116:117]
	v_lshl_add_u64 v[112:113], s[24:25], 0, v[112:113]
	v_lshl_add_u64 v[112:113], v[112:113], 0, s[28:29]
	s_or_b64 exec, exec, s[8:9]
	v_or_b32_sdwa v107, s35, v1 dst_sel:DWORD dst_unused:UNUSED_PAD src0_sel:DWORD src1_sel:BYTE_0
	v_cvt_f64_u32_e32 v[114:115], v107
	v_cvt_f32_u32_e32 v109, v107
	v_mul_f64 v[116:117], v[114:115], s[30:31]
	v_rndne_f64_e32 v[116:117], v[116:117]
	v_fma_f64 v[114:115], v[114:115], s[30:31], -v[116:117]
	v_cvt_f32_f64_e32 v107, v[114:115]
	v_sin_f32_e32 v114, v107
	v_cos_f32_e32 v116, v107
	v_mul_f32_e32 v107, 0x3e4693af, v109
	v_cvt_f64_f32_e32 v[118:119], v107
	v_mul_f64 v[120:121], v[118:119], s[30:31]
	v_rndne_f64_e32 v[120:121], v[120:121]
	v_fma_f64 v[118:119], v[118:119], s[30:31], -v[120:121]
	s_waitcnt vmcnt(21)
	v_lshlrev_b32_e32 v122, 16, v90
	v_and_b32_e32 v123, 0xffff0000, v90
	v_mul_f32_e32 v90, 0x3d1a08c8, v109
	v_cvt_f32_f64_e32 v107, v[118:119]
	v_cvt_f64_f32_e32 v[118:119], v90
	v_mul_f64 v[120:121], v[118:119], s[30:31]
	v_rndne_f64_e32 v[120:121], v[120:121]
	v_fma_f64 v[118:119], v[118:119], s[30:31], -v[120:121]
	v_cvt_f32_f64_e32 v90, v[118:119]
	v_sin_f32_e32 v118, v90
	v_cos_f32_e32 v120, v90
	v_mul_f32_e32 v90, 0x3beef74e, v109
	v_cvt_f64_f32_e32 v[126:127], v90
	v_mul_f64 v[128:129], v[126:127], s[30:31]
	v_rndne_f64_e32 v[128:129], v[128:129]
	v_fma_f64 v[126:127], v[126:127], s[30:31], -v[128:129]
	v_cvt_f32_f64_e32 v90, v[126:127]
	v_sin_f32_e32 v119, v90
	v_cos_f32_e32 v121, v90
	v_mul_f32_e32 v90, 0x3ab95d22, v109
	v_lshlrev_b32_e32 v126, 16, v91
	v_and_b32_e32 v127, 0xffff0000, v91
	v_cvt_f64_f32_e32 v[90:91], v90
	s_waitcnt vmcnt(20)
	v_lshlrev_b32_e32 v124, 16, v94
	v_and_b32_e32 v125, 0xffff0000, v94
	v_lshlrev_b32_e32 v128, 16, v95
	v_and_b32_e32 v129, 0xffff0000, v95
	v_mul_f64 v[94:95], v[90:91], s[30:31]
	v_rndne_f64_e32 v[94:95], v[94:95]
	v_fma_f64 v[90:91], v[90:91], s[30:31], -v[94:95]
	v_cvt_f32_f64_e32 v91, v[90:91]
	v_sin_f32_e32 v90, v91
	v_cos_f32_e32 v94, v91
	v_mul_f32_e32 v91, 0x398fc8f8, v109
	v_cvt_f64_f32_e32 v[130:131], v91
	v_mul_f64 v[132:133], v[130:131], s[30:31]
	v_rndne_f64_e32 v[132:133], v[132:133]
	v_fma_f64 v[130:131], v[130:131], s[30:31], -v[132:133]
	v_cvt_f32_f64_e32 v95, v[130:131]
	v_lshlrev_b32_e32 v130, 16, v92
	v_and_b32_e32 v131, 0xffff0000, v92
	v_mul_f32_e32 v92, 0x385f10c5, v109
	v_cvt_f64_f32_e32 v[138:139], v92
	v_mul_f64 v[158:159], v[138:139], s[30:31]
	v_rndne_f64_e32 v[158:159], v[158:159]
	v_sin_f32_e32 v115, v107
	v_cos_f32_e32 v117, v107
	v_fma_f64 v[138:139], v[138:139], s[30:31], -v[158:159]
	v_mul_f32_e32 v107, 0x372d07a8, v109
	v_lshlrev_b32_e32 v132, 16, v96
	v_and_b32_e32 v133, 0xffff0000, v96
	v_cvt_f32_f64_e32 v96, v[138:139]
	v_cvt_f64_f32_e32 v[138:139], v107
	v_mul_f64 v[158:159], v[138:139], s[30:31]
	v_pk_mul_f32 v[136:137], v[124:125], v[124:125]
	v_rndne_f64_e32 v[158:159], v[158:159]
	v_pk_mul_f32 v[150:151], v[128:129], v[128:129]
	v_fma_f64 v[158:159], v[138:139], s[30:31], -v[158:159]
	v_lshlrev_b32_e32 v138, 16, v93
	v_and_b32_e32 v139, 0xffff0000, v93
	v_add_f32_e32 v93, v136, v137
	v_add_f32_e32 v93, v150, v93
	v_pk_mul_f32 v[154:155], v[132:133], v[132:133]
	v_add_f32_e32 v93, v151, v93
	v_lshlrev_b32_e32 v160, 16, v97
	v_and_b32_e32 v161, 0xffff0000, v97
	v_add_f32_e32 v93, v154, v93
	v_pk_mul_f32 v[162:163], v[160:161], v[160:161]
	v_add_f32_e32 v93, v155, v93
	v_add_f32_e32 v93, v162, v93
	v_pk_mul_f32 v[134:135], v[122:123], v[122:123]
	v_add_f32_e32 v93, v163, v93
	v_add_f32_e32 v93, v134, v93
	v_pk_mul_f32 v[152:153], v[126:127], v[126:127]
	v_add_f32_e32 v93, v135, v93
	v_add_f32_e32 v93, v152, v93
	v_pk_mul_f32 v[156:157], v[130:131], v[130:131]
	v_add_f32_e32 v93, v153, v93
	v_add_f32_e32 v93, v156, v93
	v_pk_mul_f32 v[164:165], v[138:139], v[138:139]
	v_add_f32_e32 v93, v157, v93
	v_lshlrev_b32_e32 v166, 16, v86
	v_and_b32_e32 v167, 0xffff0000, v86
	v_add_f32_e32 v93, v164, v93
	v_pk_mul_f32 v[168:169], v[166:167], v[166:167]
	v_add_f32_e32 v93, v165, v93
	v_lshlrev_b32_e32 v86, 16, v87
	v_and_b32_e32 v87, 0xffff0000, v87
	v_add_f32_e32 v93, v168, v93
	v_pk_mul_f32 v[170:171], v[86:87], v[86:87]
	v_add_f32_e32 v93, v169, v93
	v_lshlrev_b32_e32 v172, 16, v88
	v_and_b32_e32 v173, 0xffff0000, v88
	v_add_f32_e32 v93, v170, v93
	v_pk_mul_f32 v[174:175], v[172:173], v[172:173]
	v_add_f32_e32 v93, v171, v93
	v_lshlrev_b32_e32 v88, 16, v89
	v_and_b32_e32 v89, 0xffff0000, v89
	v_add_f32_e32 v93, v174, v93
	v_pk_mul_f32 v[176:177], v[88:89], v[88:89]
	v_add_f32_e32 v93, v175, v93
	v_lshlrev_b32_e32 v178, 16, v82
	v_and_b32_e32 v179, 0xffff0000, v82
	v_add_f32_e32 v93, v176, v93
	v_pk_mul_f32 v[180:181], v[178:179], v[178:179]
	v_add_f32_e32 v93, v177, v93
	v_lshlrev_b32_e32 v82, 16, v83
	v_and_b32_e32 v83, 0xffff0000, v83
	v_add_f32_e32 v93, v180, v93
	v_pk_mul_f32 v[182:183], v[82:83], v[82:83]
	v_add_f32_e32 v93, v181, v93
	v_lshlrev_b32_e32 v184, 16, v84
	v_and_b32_e32 v185, 0xffff0000, v84
	v_add_f32_e32 v93, v182, v93
	v_pk_mul_f32 v[186:187], v[184:185], v[184:185]
	v_add_f32_e32 v93, v183, v93
	v_lshlrev_b32_e32 v84, 16, v85
	v_and_b32_e32 v85, 0xffff0000, v85
	v_add_f32_e32 v93, v186, v93
	v_pk_mul_f32 v[188:189], v[84:85], v[84:85]
	v_add_f32_e32 v93, v187, v93
	s_waitcnt vmcnt(16)
	v_lshlrev_b32_e32 v190, 16, v78
	v_and_b32_e32 v191, 0xffff0000, v78
	v_add_f32_e32 v93, v188, v93
	v_pk_mul_f32 v[192:193], v[190:191], v[190:191]
	v_add_f32_e32 v93, v189, v93
	v_lshlrev_b32_e32 v78, 16, v79
	v_and_b32_e32 v79, 0xffff0000, v79
	v_add_f32_e32 v93, v192, v93
	v_pk_mul_f32 v[194:195], v[78:79], v[78:79]
	v_add_f32_e32 v93, v193, v93
	v_lshlrev_b32_e32 v196, 16, v80
	v_and_b32_e32 v197, 0xffff0000, v80
	v_add_f32_e32 v93, v194, v93
	v_pk_mul_f32 v[198:199], v[196:197], v[196:197]
	v_add_f32_e32 v93, v195, v93
	v_lshlrev_b32_e32 v80, 16, v81
	v_and_b32_e32 v81, 0xffff0000, v81
	v_add_f32_e32 v93, v198, v93
	v_pk_mul_f32 v[200:201], v[80:81], v[80:81]
	v_add_f32_e32 v93, v199, v93
	v_lshlrev_b32_e32 v202, 16, v74
	v_and_b32_e32 v203, 0xffff0000, v74
	v_add_f32_e32 v93, v200, v93
	v_pk_mul_f32 v[204:205], v[202:203], v[202:203]
	v_add_f32_e32 v93, v201, v93
	v_lshlrev_b32_e32 v74, 16, v75
	v_and_b32_e32 v75, 0xffff0000, v75
	v_add_f32_e32 v93, v204, v93
	v_pk_mul_f32 v[206:207], v[74:75], v[74:75]
	v_add_f32_e32 v93, v205, v93
	v_lshlrev_b32_e32 v208, 16, v76
	v_and_b32_e32 v209, 0xffff0000, v76
	v_add_f32_e32 v93, v206, v93
	v_pk_mul_f32 v[210:211], v[208:209], v[208:209]
	v_add_f32_e32 v93, v207, v93
	v_lshlrev_b32_e32 v76, 16, v77
	v_and_b32_e32 v77, 0xffff0000, v77
	v_add_f32_e32 v93, v210, v93
	v_pk_mul_f32 v[212:213], v[76:77], v[76:77]
	v_add_f32_e32 v93, v211, v93
	v_lshlrev_b32_e32 v214, 16, v70
	v_and_b32_e32 v215, 0xffff0000, v70
	v_add_f32_e32 v93, v212, v93
	v_pk_mul_f32 v[216:217], v[214:215], v[214:215]
	v_add_f32_e32 v93, v213, v93
	v_lshlrev_b32_e32 v70, 16, v71
	v_and_b32_e32 v71, 0xffff0000, v71
	v_add_f32_e32 v93, v216, v93
	v_pk_mul_f32 v[218:219], v[70:71], v[70:71]
	v_add_f32_e32 v93, v217, v93
	v_lshlrev_b32_e32 v220, 16, v72
	v_and_b32_e32 v221, 0xffff0000, v72
	v_add_f32_e32 v93, v218, v93
	v_pk_mul_f32 v[222:223], v[220:221], v[220:221]
	v_add_f32_e32 v93, v219, v93
	v_lshlrev_b32_e32 v72, 16, v73
	v_and_b32_e32 v73, 0xffff0000, v73
	v_add_f32_e32 v93, v222, v93
	v_pk_mul_f32 v[224:225], v[72:73], v[72:73]
	v_add_f32_e32 v93, v223, v93
	v_lshlrev_b32_e32 v226, 16, v66
	v_and_b32_e32 v227, 0xffff0000, v66
	v_add_f32_e32 v93, v224, v93
	v_pk_mul_f32 v[228:229], v[226:227], v[226:227]
	v_add_f32_e32 v93, v225, v93
	v_lshlrev_b32_e32 v66, 16, v67
	v_and_b32_e32 v67, 0xffff0000, v67
	v_add_f32_e32 v93, v228, v93
	v_pk_mul_f32 v[230:231], v[66:67], v[66:67]
	v_add_f32_e32 v93, v229, v93
	v_lshlrev_b32_e32 v232, 16, v68
	v_and_b32_e32 v233, 0xffff0000, v68
	v_add_f32_e32 v93, v230, v93
	v_pk_mul_f32 v[234:235], v[232:233], v[232:233]
	v_add_f32_e32 v93, v231, v93
	v_lshlrev_b32_e32 v68, 16, v69
	v_and_b32_e32 v69, 0xffff0000, v69
	v_add_f32_e32 v93, v234, v93
	v_pk_mul_f32 v[236:237], v[68:69], v[68:69]
	v_add_f32_e32 v93, v235, v93
	v_add_f32_e32 v93, v236, v93
	v_add_f32_e32 v93, v237, v93
	v_fmamk_f32 v93, v93, 0x3c800000, v144
	v_mul_f32_e32 v97, 0x4b800000, v93
	v_cmp_gt_f32_e64 s[8:9], s39, v93
	v_sin_f32_e32 v91, v95
	v_sin_f32_e32 v92, v96
	v_cndmask_b32_e64 v93, v93, v97, s[8:9]
	v_rsq_f32_e32 v107, v93
	v_cvt_f32_f64_e32 v97, v[158:159]
	v_sin_f32_e32 v93, v97
	v_cos_f32_e32 v95, v95
	v_mul_f32_e32 v109, 0x45800000, v107
	v_cndmask_b32_e64 v134, v107, v109, s[8:9]
	v_pk_mul_f32 v[124:125], v[134:135], v[124:125] op_sel_hi:[0,1]
	s_waitcnt vmcnt(12)
	v_pk_mul_f32 v[62:63], v[62:63], v[124:125]
	v_pk_mul_f32 v[124:125], v[134:135], v[128:129] op_sel_hi:[0,1]
	v_pk_mul_f32 v[64:65], v[64:65], v[124:125]
	v_pk_mul_f32 v[124:125], v[134:135], v[132:133] op_sel_hi:[0,1]
	v_pk_mul_f32 v[58:59], v[58:59], v[124:125]
	v_pk_mul_f32 v[124:125], v[134:135], v[160:161] op_sel_hi:[0,1]
	v_pk_mul_f32 v[124:125], v[60:61], v[124:125]
	v_pk_mul_f32 v[60:61], v[134:135], v[122:123] op_sel_hi:[0,1]
	v_pk_mul_f32 v[54:55], v[54:55], v[60:61]
	v_pk_mul_f32 v[60:61], v[134:135], v[126:127] op_sel_hi:[0,1]
	v_pk_mul_f32 v[60:61], v[56:57], v[60:61]
	v_pk_mul_f32 v[56:57], v[134:135], v[130:131] op_sel_hi:[0,1]
	v_pk_mul_f32 v[122:123], v[46:47], v[56:57]
	v_pk_mul_f32 v[46:47], v[134:135], v[138:139] op_sel_hi:[0,1]
	v_pk_mul_f32 v[126:127], v[48:49], v[46:47]
	v_pk_mul_f32 v[46:47], v[134:135], v[166:167] op_sel_hi:[0,1]
	s_waitcnt vmcnt(8)
	v_pk_mul_f32 v[46:47], v[50:51], v[46:47]
	v_pk_mul_f32 v[50:51], v[134:135], v[172:173] op_sel_hi:[0,1]
	v_pk_mul_f32 v[42:43], v[42:43], v[50:51]
	v_pk_mul_f32 v[50:51], v[134:135], v[88:89] op_sel_hi:[0,1]
	v_pk_mul_f32 v[44:45], v[44:45], v[50:51]
	v_pk_mul_f32 v[50:51], v[134:135], v[178:179] op_sel_hi:[0,1]
	v_pk_mul_f32 v[38:39], v[38:39], v[50:51]
	v_pk_mul_f32 v[50:51], v[134:135], v[82:83] op_sel_hi:[0,1]
	v_pk_mul_f32 v[40:41], v[40:41], v[50:51]
	v_pk_mul_f32 v[50:51], v[134:135], v[184:185] op_sel_hi:[0,1]
	v_pk_mul_f32 v[30:31], v[30:31], v[50:51]
	v_pk_mul_f32 v[50:51], v[134:135], v[84:85] op_sel_hi:[0,1]
	v_pk_mul_f32 v[32:33], v[32:33], v[50:51]
	v_pk_mul_f32 v[50:51], v[134:135], v[190:191] op_sel_hi:[0,1]
	s_waitcnt vmcnt(4)
	v_pk_mul_f32 v[34:35], v[34:35], v[50:51]
	v_pk_mul_f32 v[50:51], v[134:135], v[78:79] op_sel_hi:[0,1]
	v_pk_mul_f32 v[36:37], v[36:37], v[50:51]
	v_pk_mul_f32 v[50:51], v[134:135], v[196:197] op_sel_hi:[0,1]
	v_pk_mul_f32 v[26:27], v[26:27], v[50:51]
	v_pk_mul_f32 v[50:51], v[134:135], v[80:81] op_sel_hi:[0,1]
	v_pk_mul_f32 v[28:29], v[28:29], v[50:51]
	v_pk_mul_f32 v[50:51], v[134:135], v[202:203] op_sel_hi:[0,1]
	v_pk_mul_f32 v[22:23], v[22:23], v[50:51]
	v_pk_mul_f32 v[50:51], v[134:135], v[74:75] op_sel_hi:[0,1]
	v_pk_mul_f32 v[24:25], v[24:25], v[50:51]
	v_pk_mul_f32 v[50:51], v[134:135], v[208:209] op_sel_hi:[0,1]
	v_pk_mul_f32 v[14:15], v[14:15], v[50:51]
	v_pk_mul_f32 v[50:51], v[134:135], v[76:77] op_sel_hi:[0,1]
	v_pk_mul_f32 v[16:17], v[16:17], v[50:51]
	v_pk_mul_f32 v[50:51], v[134:135], v[214:215] op_sel_hi:[0,1]
	s_waitcnt vmcnt(0)
	v_pk_mul_f32 v[18:19], v[18:19], v[50:51]
	v_pk_mul_f32 v[50:51], v[134:135], v[70:71] op_sel_hi:[0,1]
	v_pk_mul_f32 v[20:21], v[20:21], v[50:51]
	v_pk_mul_f32 v[50:51], v[134:135], v[220:221] op_sel_hi:[0,1]
	v_pk_mul_f32 v[10:11], v[10:11], v[50:51]
	v_pk_mul_f32 v[50:51], v[134:135], v[72:73] op_sel_hi:[0,1]
	v_pk_mul_f32 v[12:13], v[12:13], v[50:51]
	v_pk_mul_f32 v[50:51], v[134:135], v[226:227] op_sel_hi:[0,1]
	v_pk_mul_f32 v[6:7], v[6:7], v[50:51]
	v_pk_mul_f32 v[50:51], v[134:135], v[66:67] op_sel_hi:[0,1]
	v_pk_mul_f32 v[8:9], v[8:9], v[50:51]
	v_pk_mul_f32 v[50:51], v[134:135], v[232:233] op_sel_hi:[0,1]
	v_pk_mul_f32 v[2:3], v[2:3], v[50:51]
	v_pk_mul_f32 v[50:51], v[134:135], v[68:69] op_sel_hi:[0,1]
	v_pk_mul_f32 v[48:49], v[134:135], v[86:87] op_sel_hi:[0,1]
	v_pk_mul_f32 v[4:5], v[4:5], v[50:51]
	v_pk_mul_f32 v[50:51], v[114:115], v[54:55]
	v_cos_f32_e32 v96, v96
	v_cos_f32_e32 v97, v97
	v_pk_mul_f32 v[48:49], v[52:53], v[48:49]
	v_pk_fma_f32 v[52:53], v[116:117], v[62:63], v[50:51] neg_lo:[0,0,1] neg_hi:[0,0,1]
	v_pk_mul_f32 v[50:51], v[114:115], v[62:63]
	v_pk_mul_f32 v[62:63], v[92:93], v[126:127]
	v_pk_fma_f32 v[50:51], v[116:117], v[54:55], v[50:51]
	v_pk_mul_f32 v[54:55], v[118:119], v[60:61]
	v_lshl_add_u64 v[70:71], v[112:113], 0, s[20:21]
	v_pk_fma_f32 v[56:57], v[120:121], v[64:65], v[54:55] neg_lo:[0,0,1] neg_hi:[0,0,1]
	v_pk_mul_f32 v[54:55], v[118:119], v[64:65]
	v_pk_fma_f32 v[64:65], v[96:97], v[124:125], v[62:63] neg_lo:[0,0,1] neg_hi:[0,0,1]
	v_pk_fma_f32 v[54:55], v[120:121], v[60:61], v[54:55]
	v_pk_mul_f32 v[60:61], v[90:91], v[122:123]
	v_pk_mul_f32 v[62:63], v[92:93], v[124:125]
	v_pk_fma_f32 v[60:61], v[94:95], v[58:59], v[60:61] neg_lo:[0,0,1] neg_hi:[0,0,1]
	v_pk_mul_f32 v[58:59], v[90:91], v[58:59]
	v_pk_fma_f32 v[62:63], v[96:97], v[126:127], v[62:63]
	v_pk_fma_f32 v[58:59], v[94:95], v[122:123], v[58:59]
	v_readfirstlane_b32 s46, v1
	v_and_b32_e32 v239, 63, v1
	s_lshr_b32 s47, s46, 6
	s_cmpk_gt_u32 s46, 0xff
	s_movk_i32 s44, 0x4000
	s_cselect_b32 s44, 0x2000, s44
	s_mov_b32 s45, 0
	s_mul_i32 s48, s47, 0x2400
	s_add_i32 s48, s48, 0x19000
	s_sub_i32 s49, s47, 4
	s_mul_i32 s49, s49, 0x4100
	s_cmpk_gt_u32 s46, 0xff
	s_cselect_b32 s48, s49, s48
	v_mul_u32_u24_e32 v238, 0x90, v239
	v_lshrrev_b32_e32 v240, 3, v239
	v_and_b32_e32 v241, 7, v239
	v_add_u32_e32 v238, s48, v238
	v_mul_u32_u24_e32 v239, 0x90, v240
	s_lshr_b32 s49, s44, 3
	v_lshl_add_u32 v239, v241, 4, v239
	v_mul_lo_u32 v240, v240, s49
	v_readfirstlane_b32 s42, v70
	v_readfirstlane_b32 s43, v71
	v_add_u32_e32 v239, s48, v239
	v_lshl_add_u32 v240, v241, 4, v240
	v_mov_b32_e32 v241, 0
	s_nop 1
	v_lshl_add_u64 v[240:241], s[42:43], 0, v[240:241]
	v_cvt_pk_bf16_f32 v66, v52, v53
	v_cvt_pk_bf16_f32 v67, v56, v57
	v_cvt_pk_bf16_f32 v68, v60, v61
	v_cvt_pk_bf16_f32 v69, v64, v65
	ds_write_b128 v238, v[66:69]
	s_nop 1
	v_cvt_pk_bf16_f32 v66, v50, v51
	v_cvt_pk_bf16_f32 v67, v54, v55
	v_cvt_pk_bf16_f32 v68, v58, v59
	v_cvt_pk_bf16_f32 v69, v62, v63
	ds_write_b128 v238, v[66:69] offset:16
	s_nop 1
	v_cvt_pk_bf16_f32 v66, v46, v47
	v_cvt_pk_bf16_f32 v67, v48, v49
	v_cvt_pk_bf16_f32 v68, v42, v43
	v_cvt_pk_bf16_f32 v69, v44, v45
	ds_write_b128 v238, v[66:69] offset:32
	s_nop 1
	v_cvt_pk_bf16_f32 v66, v38, v39
	v_cvt_pk_bf16_f32 v67, v40, v41
	v_cvt_pk_bf16_f32 v68, v30, v31
	v_cvt_pk_bf16_f32 v69, v32, v33
	ds_write_b128 v238, v[66:69] offset:48
	s_nop 1
	v_cvt_pk_bf16_f32 v66, v34, v35
	v_cvt_pk_bf16_f32 v67, v36, v37
	v_cvt_pk_bf16_f32 v68, v26, v27
	v_cvt_pk_bf16_f32 v69, v28, v29
	ds_write_b128 v238, v[66:69] offset:64
	s_nop 1
	v_cvt_pk_bf16_f32 v66, v22, v23
	v_cvt_pk_bf16_f32 v67, v24, v25
	v_cvt_pk_bf16_f32 v68, v14, v15
	v_cvt_pk_bf16_f32 v69, v16, v17
	ds_write_b128 v238, v[66:69] offset:80
	s_nop 1
	v_cvt_pk_bf16_f32 v66, v18, v19
	v_cvt_pk_bf16_f32 v67, v20, v21
	v_cvt_pk_bf16_f32 v68, v10, v11
	v_cvt_pk_bf16_f32 v69, v12, v13
	ds_write_b128 v238, v[66:69] offset:96
	s_nop 1
	v_cvt_pk_bf16_f32 v66, v6, v7
	v_cvt_pk_bf16_f32 v67, v8, v9
	v_cvt_pk_bf16_f32 v68, v2, v3
	v_cvt_pk_bf16_f32 v69, v4, v5
	ds_write_b128 v238, v[66:69] offset:112
	s_waitcnt lgkmcnt(0)
	ds_read_b128 v[242:245], v239
	ds_read_b128 v[66:69], v239 offset:1152
	s_waitcnt lgkmcnt(1)
	global_store_dwordx4 v[240:241], v[242:245], off
	v_lshl_add_u64 v[240:241], v[240:241], 0, s[44:45]
	s_nop 1
	ds_read_b128 v[242:245], v239 offset:2304
	s_waitcnt lgkmcnt(1)
	global_store_dwordx4 v[240:241], v[66:69], off
	v_lshl_add_u64 v[240:241], v[240:241], 0, s[44:45]
	s_nop 1
	ds_read_b128 v[66:69], v239 offset:3456
	s_waitcnt lgkmcnt(1)
	global_store_dwordx4 v[240:241], v[242:245], off
	v_lshl_add_u64 v[240:241], v[240:241], 0, s[44:45]
	s_nop 1
	ds_read_b128 v[242:245], v239 offset:4608
	s_waitcnt lgkmcnt(1)
	global_store_dwordx4 v[240:241], v[66:69], off
	v_lshl_add_u64 v[240:241], v[240:241], 0, s[44:45]
	s_nop 1
	ds_read_b128 v[66:69], v239 offset:5760
	s_waitcnt lgkmcnt(1)
	global_store_dwordx4 v[240:241], v[242:245], off
	v_lshl_add_u64 v[240:241], v[240:241], 0, s[44:45]
	s_nop 1
	ds_read_b128 v[242:245], v239 offset:6912
	s_waitcnt lgkmcnt(1)
	global_store_dwordx4 v[240:241], v[66:69], off
	v_lshl_add_u64 v[240:241], v[240:241], 0, s[44:45]
	s_nop 1
	ds_read_b128 v[66:69], v239 offset:8064
	s_waitcnt lgkmcnt(1)
	global_store_dwordx4 v[240:241], v[242:245], off
	v_lshl_add_u64 v[240:241], v[240:241], 0, s[44:45]
	s_waitcnt lgkmcnt(0)
	global_store_dwordx4 v[240:241], v[66:69], off
	s_nop 1
	s_and_saveexec_b64 s[8:9], s[4:5]
	s_cbranch_execz .LBB0_400
	ds_write2_b32 v145, v52, v53 offset1:1
	ds_write2_b32 v145, v56, v57 offset0:2 offset1:3
	ds_write2_b32 v145, v60, v61 offset0:4 offset1:5
	ds_write2_b32 v145, v64, v65 offset0:6 offset1:7
	ds_write2_b32 v145, v50, v51 offset0:8 offset1:9
	ds_write2_b32 v145, v54, v55 offset0:10 offset1:11
	ds_write2_b32 v145, v58, v59 offset0:12 offset1:13
	ds_write2_b32 v145, v62, v63 offset0:14 offset1:15
	ds_write2_b32 v145, v46, v47 offset0:16 offset1:17
	ds_write2_b32 v145, v48, v49 offset0:18 offset1:19
	ds_write2_b32 v145, v42, v43 offset0:20 offset1:21
	ds_write2_b32 v145, v44, v45 offset0:22 offset1:23
	ds_write2_b32 v145, v38, v39 offset0:24 offset1:25
	ds_write2_b32 v145, v40, v41 offset0:26 offset1:27
	ds_write2_b32 v145, v30, v31 offset0:28 offset1:29
	ds_write2_b32 v145, v32, v33 offset0:30 offset1:31
	ds_write2_b32 v145, v34, v35 offset0:32 offset1:33
	ds_write2_b32 v145, v36, v37 offset0:34 offset1:35
	ds_write2_b32 v145, v26, v27 offset0:36 offset1:37
	ds_write2_b32 v145, v28, v29 offset0:38 offset1:39
	ds_write2_b32 v145, v22, v23 offset0:40 offset1:41
	ds_write2_b32 v145, v24, v25 offset0:42 offset1:43
	ds_write2_b32 v145, v14, v15 offset0:44 offset1:45
	ds_write2_b32 v145, v16, v17 offset0:46 offset1:47
	ds_write2_b32 v145, v18, v19 offset0:48 offset1:49
	ds_write2_b32 v145, v20, v21 offset0:50 offset1:51
	ds_write2_b32 v145, v10, v11 offset0:52 offset1:53
	ds_write2_b32 v145, v12, v13 offset0:54 offset1:55
	ds_write2_b32 v145, v6, v7 offset0:56 offset1:57
	ds_write2_b32 v145, v8, v9 offset0:58 offset1:59
	ds_write2_b32 v145, v2, v3 offset0:60 offset1:61
	ds_write2_b32 v145, v4, v5 offset0:62 offset1:63
